# v48 + gated-conv unit: 8th per-row gate load also hoisted to unit start (load hoisting completes; tail wait removed)
# baseline (speedup 1.0000x reference)
.LBB0_126:
	s_or_b64 exec, exec, s[8:9]
	v_mad_i64_i32 v[30:31], s[6:7], v26, s47, v[30:31]
	v_mov_b32_e32 v56, v122
	v_mov_b32_e32 v57, v123
	v_mov_b32_e32 v58, v124
	v_mov_b32_e32 v59, v125
	v_ashrrev_i32_e32 v27, 31, v26
	v_pk_mul_f32 v[22:23], v[22:23], v[54:55]
	v_pk_mul_f32 v[24:25], v[24:25], v[50:51]
	v_pk_mul_f32 v[18:19], v[18:19], v[42:43]
	v_pk_mul_f32 v[20:21], v[20:21], v[36:37]
	v_pk_fma_f32 v[14:15], v[14:15], v[52:53], v[22:23]
	v_pk_fma_f32 v[16:17], v[16:17], v[38:39], v[24:25]
	v_pk_fma_f32 v[10:11], v[10:11], v[44:45], v[18:19]
	v_pk_fma_f32 v[12:13], v[12:13], v[34:35], v[20:21]
	v_lshlrev_b64 v[18:19], 11, v[26:27]
	v_pk_fma_f32 v[6:7], v[6:7], v[32:33], v[14:15]
	v_pk_fma_f32 v[8:9], v[8:9], v[46:47], v[16:17]
	v_pk_fma_f32 v[2:3], v[2:3], v[48:49], v[10:11]
	v_pk_fma_f32 v[4:5], v[4:5], v[40:41], v[12:13]
	v_lshl_add_u64 v[10:11], v[28:29], 0, v[18:19]
	s_add_i32 s0, s0, s56
	s_add_i32 s11, s11, s72
	s_cmpk_gt_i32 s0, 0x1ff
	v_lshlrev_b32_e32 v12, 16, v56
	v_and_b32_e32 v13, 0xffff0000, v56
	v_lshlrev_b32_e32 v14, 16, v57
	v_and_b32_e32 v15, 0xffff0000, v57
	v_lshlrev_b32_e32 v16, 16, v58
	v_and_b32_e32 v17, 0xffff0000, v58
	v_lshlrev_b32_e32 v18, 16, v59
	v_and_b32_e32 v19, 0xffff0000, v59
	v_pk_mul_f32 v[6:7], v[6:7], v[12:13]
	v_pk_mul_f32 v[8:9], v[8:9], v[14:15]
	v_pk_mul_f32 v[12:13], v[2:3], v[16:17]
	v_pk_mul_f32 v[14:15], v[4:5], v[18:19]
	v_cvt_pk_bf16_f32 v2, v6, v7
	v_cvt_pk_bf16_f32 v3, v8, v9
	v_cvt_pk_bf16_f32 v4, v12, v13
	v_cvt_pk_bf16_f32 v5, v14, v15
	global_store_dwordx4 v[10:11], v[2:5], off
	s_cbranch_scc1 .LBB0_147
.LBB0_127:
	v_mov_b32_e32 v26, v243
	s_load_dwordx2 s[6:7], s[58:59], 0x38
	v_lshlrev_b32_e32 v0, 3, v26
	v_and_b32_e32 v28, 0x1f8, v0
	v_lshlrev_b32_e32 v0, 2, v28
	s_mov_b64 s[8:9], 0x1000
	s_waitcnt lgkmcnt(0)
	s_add_u32 s6, s6, s10
	s_addc_u32 s7, s7, s1
	v_lshl_add_u64 v[18:19], s[6:7], 0, v[0:1]
	v_lshl_add_u64 v[20:21], v[18:19], 0, s[8:9]
	global_load_dwordx4 v[2:5], v0, s[6:7] offset:16
	global_load_dwordx4 v[6:9], v0, s[6:7]
	global_load_dwordx4 v[10:13], v0, s[6:7] offset:2064
	global_load_dwordx4 v[14:17], v0, s[6:7] offset:2048
	v_add_co_u32_e32 v18, vcc, s75, v18
	v_ashrrev_i32_e32 v0, 3, v26
	s_nop 0
	v_addc_co_u32_e32 v19, vcc, 0, v19, vcc
	global_load_dwordx4 v[22:25], v[18:19], off
	s_nop 0
	global_load_dwordx4 v[18:21], v[20:21], off offset:16
	v_and_b32_e32 v0, -8, v0
	v_add_u32_e32 v26, s11, v0
	s_movk_i32 s6, 0xff8
	v_add_u32_e32 v27, -2, v26
	v_and_or_b32 v60, v26, s6, 7
	v_and_b32_e32 v0, 0xffe, v27
	v_cmp_lt_i32_e32 vcc, 1, v26
	v_cmp_le_u32_e64 s[38:39], v0, v60
	s_and_b64 s[8:9], vcc, s[38:39]
	v_mov_b32_e32 v40, 0
	v_lshlrev_b32_e32 v0, 1, v28
	v_mov_b32_e32 v56, 0
	v_mov_b32_e32 v57, 0
	v_mov_b32_e32 v48, 0
	v_mov_b32_e32 v49, 0
	v_mov_b32_e32 v42, 0
	v_mov_b32_e32 v43, 0
	v_mov_b32_e32 v36, 0
	v_mov_b32_e32 v37, 0
	v_lshl_add_u64 v[66:67], s[2:3], 0, v[0:1]
	v_mad_i64_i32 v[68:69], s[38:39], v26, s47, v[66:67]
	global_load_dwordx4 v[70:73], v[68:69], off
	v_add_u32_e32 v65, 1, v26
	v_mad_i64_i32 v[68:69], s[38:39], v65, s47, v[66:67]
	global_load_dwordx4 v[74:77], v[68:69], off
	v_add_u32_e32 v65, 2, v26
	v_mad_i64_i32 v[68:69], s[38:39], v65, s47, v[66:67]
	global_load_dwordx4 v[78:81], v[68:69], off
	v_add_u32_e32 v65, 3, v26
	v_mad_i64_i32 v[68:69], s[38:39], v65, s47, v[66:67]
	global_load_dwordx4 v[82:85], v[68:69], off
	v_add_u32_e32 v65, 4, v26
	v_mad_i64_i32 v[68:69], s[38:39], v65, s47, v[66:67]
	global_load_dwordx4 v[86:89], v[68:69], off
	v_add_u32_e32 v65, 5, v26
	v_mad_i64_i32 v[68:69], s[38:39], v65, s47, v[66:67]
	global_load_dwordx4 v[90:93], v[68:69], off
	v_add_u32_e32 v65, 6, v26
	v_mad_i64_i32 v[68:69], s[38:39], v65, s47, v[66:67]
	global_load_dwordx4 v[94:97], v[68:69], off
	v_add_u32_e32 v65, 7, v26
	v_mad_i64_i32 v[68:69], s[38:39], v65, s47, v[66:67]
	global_load_dwordx4 v[122:125], v[68:69], off
	s_and_saveexec_b64 s[6:7], s[8:9]
	s_cbranch_execz .LBB0_129
	v_mov_b64_e32 v[28:29], s[2:3]
	v_mad_u64_u32 v[28:29], s[8:9], v27, s47, v[28:29]
	v_lshl_add_u64 v[32:33], v[28:29], 0, v[0:1]
	global_load_dwordx4 v[28:31], v[32:33], off offset:1024
	s_nop 0
	global_load_dwordx4 v[32:35], v[32:33], off offset:2048
	s_waitcnt vmcnt(1)
	v_lshlrev_b32_e32 v38, 16, v28
	v_and_b32_e32 v39, 0xffff0000, v28
	s_waitcnt vmcnt(0)
	v_lshlrev_b32_e32 v44, 16, v32
	v_and_b32_e32 v45, 0xffff0000, v32
	v_lshlrev_b32_e32 v28, 16, v29
	v_and_b32_e32 v29, 0xffff0000, v29
	v_lshlrev_b32_e32 v32, 16, v33
	v_and_b32_e32 v33, 0xffff0000, v33
	v_lshlrev_b32_e32 v42, 16, v30
	v_and_b32_e32 v43, 0xffff0000, v30
	v_lshlrev_b32_e32 v46, 16, v34
	v_and_b32_e32 v47, 0xffff0000, v34
	v_lshlrev_b32_e32 v30, 16, v31
	v_lshlrev_b32_e32 v34, 16, v35
	v_and_b32_e32 v35, 0xffff0000, v35
	v_and_b32_e32 v31, 0xffff0000, v31
	v_pk_mul_f32 v[36:37], v[30:31], v[34:35]
	v_pk_mul_f32 v[48:49], v[28:29], v[32:33]
	v_pk_mul_f32 v[42:43], v[42:43], v[46:47]
	v_pk_mul_f32 v[56:57], v[38:39], v[44:45]
